# P0 gate/up weight-convert item remap: a workgroup's 8 items = 2 k-blocks x 4 n-blocks (512 B contiguous reads, one full 128 B line per output row) instead of 4x2
# baseline (speedup 1.0000x reference)
.LBB0_48:
	s_andn2_b64 vcc, exec, s[4:5]
	s_cbranch_vccnz .LBB0_26
	s_mul_hi_i32 s0, s68, 0x2fa0be83
	s_lshr_b32 s4, s0, 31
	s_ashr_i32 s0, s0, 12
	s_add_i32 s0, s0, s4
	s_mul_i32 s4, s0, 0xffffaa00
	s_add_i32 s4, s68, s4
	s_ashr_i32 s5, s0, 1
	s_and_b32 s8, s0, 1
	s_cmp_eq_u32 s8, 0
	s_cselect_b32 s62, s52, s54
	s_mul_hi_i32 s63, s5, 0xac00000
	s_mul_i32 s5, s5, 0xac00000
	s_cselect_b32 s9, s53, s55
	s_add_u32 s5, s62, s5
	s_addc_u32 s63, s9, s63
	s_ashr_i32 s4, s4, 3
	s_mul_hi_i32 s9, s4, 0x2fa0be83
	s_lshr_b32 s62, s9, 31
	s_ashr_i32 s9, s9, 4
	s_add_i32 s62, s9, s62
	s_mul_i32 s9, s62, 0x56
	s_sub_i32 s9, s4, s9
	s_lshl_b32 s4, s9, 7
	s_and_b32 s69, s33, 0x60
	s_or_b32 s4, s4, s69
	s_cmp_lt_u32 s0, 2
	s_cselect_b32 s0, s61, 0xb000000
	s_add_u32 s0, s64, s0
	s_addc_u32 s69, s65, 0
	s_lshl_b32 s9, s9, 8
	s_and_b32 s9, s9, 0xffffff00
	s_and_b32 s70, s4, 0x60
	s_or_b32 s9, s9, s70
	s_lshl_b32 s8, s8, 7
	s_or_b32 s8, s9, s8
	s_ashr_i32 s9, s8, 31
	s_lshl_b64 s[8:9], s[8:9], 12
	s_add_u32 s0, s0, s8
	s_addc_u32 s8, s69, s9
	s_lshl_b32 s9, s62, 7
	s_and_b32 s62, s33, 0x80
	s_lshr_b32 s62, s62, 1
	s_or_b32 s9, s9, s62
	s_ashr_i32 s62, s9, 31
	s_mul_i32 s70, s9, 0xac00
	s_mul_hi_i32 s69, s9, 0xac00
	s_add_u32 s70, s5, s70
	s_addc_u32 s63, s63, s69
	s_ashr_i32 s5, s4, 31
	s_lshl_b64 s[4:5], s[4:5], 2
	s_add_u32 s4, s70, s4
	s_addc_u32 s5, s63, s5
	s_add_u32 s70, s4, 0x15800
	s_addc_u32 s71, s5, 0
	global_load_dword v19, v33, s[4:5] nt
	global_load_dword v21, v33, s[70:71] nt
	s_add_u32 s70, s4, 0x2b000
	s_addc_u32 s71, s5, 0
	global_load_dword v23, v33, s[70:71] nt
	s_add_u32 s70, s4, 0x40800
	s_addc_u32 s71, s5, 0
	global_load_dword v25, v33, s[70:71] nt
	s_add_u32 s70, s4, 0x56000
	s_addc_u32 s71, s5, 0
	global_load_dword v42, v33, s[70:71] nt
	s_add_u32 s70, s4, 0x6b800
	s_addc_u32 s71, s5, 0
	global_load_dword v43, v33, s[70:71] nt
	s_add_u32 s70, s4, 0x81000
	s_addc_u32 s71, s5, 0
	global_load_dword v44, v33, s[70:71] nt
	s_add_u32 s70, s4, 0x96800
	s_addc_u32 s71, s5, 0
	global_load_dword v45, v33, s[70:71] nt
	s_add_u32 s70, s4, 0xac000
	s_addc_u32 s71, s5, 0
	global_load_dword v46, v33, s[70:71] nt
	s_add_u32 s70, s4, 0xc1800
	s_addc_u32 s71, s5, 0
	global_load_dword v47, v33, s[70:71] nt
	s_add_u32 s70, s4, 0xd7000
	s_addc_u32 s71, s5, 0
	global_load_dword v48, v33, s[70:71] nt
	s_add_u32 s70, s4, 0xec800
	s_addc_u32 s71, s5, 0
	global_load_dword v49, v33, s[70:71] nt
	s_add_u32 s70, s4, 0x102000
	s_addc_u32 s71, s5, 0
	global_load_dword v50, v33, s[70:71] nt
	s_add_u32 s70, s4, 0x117800
	s_addc_u32 s71, s5, 0
	global_load_dword v51, v33, s[70:71] nt
	s_add_u32 s70, s4, 0x12d000
	s_addc_u32 s71, s5, 0
	global_load_dword v52, v33, s[70:71] nt
	s_add_u32 s70, s4, 0x142800
	s_addc_u32 s71, s5, 0
	global_load_dword v53, v33, s[70:71] nt
	s_add_u32 s70, s4, 0x158000
	s_addc_u32 s71, s5, 0
	global_load_dword v54, v33, s[70:71] nt
	s_add_u32 s70, s4, 0x16d800
	s_addc_u32 s71, s5, 0
	global_load_dword v55, v33, s[70:71] nt
	s_add_u32 s70, s4, 0x183000
	s_addc_u32 s71, s5, 0
	global_load_dword v56, v33, s[70:71] nt
	s_add_u32 s70, s4, 0x198800
	s_addc_u32 s71, s5, 0
	global_load_dword v57, v33, s[70:71] nt
	s_add_u32 s70, s4, 0x1ae000
	s_addc_u32 s71, s5, 0
	global_load_dword v58, v33, s[70:71] nt
	s_add_u32 s70, s4, 0x1c3800
	s_addc_u32 s71, s5, 0
	global_load_dword v59, v33, s[70:71] nt
	s_add_u32 s70, s4, 0x1d9000
	s_addc_u32 s71, s5, 0
	global_load_dword v60, v33, s[70:71] nt
	s_add_u32 s70, s4, 0x1ee800
	s_addc_u32 s71, s5, 0
	global_load_dword v61, v33, s[70:71] nt
	s_add_u32 s70, s4, 0x204000
	s_addc_u32 s71, s5, 0
	global_load_dword v62, v33, s[70:71] nt
	s_add_u32 s70, s4, 0x219800
	s_addc_u32 s71, s5, 0
	global_load_dword v63, v33, s[70:71] nt
	s_add_u32 s70, s4, 0x22f000
	s_addc_u32 s71, s5, 0
	global_load_dword v64, v33, s[70:71] nt
	s_add_u32 s70, s4, 0x244800
	s_addc_u32 s71, s5, 0
	global_load_dword v65, v33, s[70:71] nt
	s_add_u32 s70, s4, 0x25a000
	s_addc_u32 s71, s5, 0
	global_load_dword v66, v33, s[70:71] nt
	s_add_u32 s70, s4, 0x26f800
	s_addc_u32 s71, s5, 0
	global_load_dword v67, v33, s[70:71] nt
	s_add_u32 s70, s4, 0x285000
	s_addc_u32 s71, s5, 0
	s_add_u32 s4, s4, 0x29a800
	global_load_dword v68, v33, s[70:71] nt
	s_addc_u32 s5, s5, 0
	global_load_dword v69, v33, s[4:5] nt
	s_waitcnt vmcnt(0)
	s_add_u32 s4, s0, s9
	ds_write2_b32 v30, v19, v21 offset1:66
	ds_write2_b32 v30, v23, v25 offset0:132 offset1:198
	ds_write2_b32 v34, v42, v43 offset0:8 offset1:74
	ds_write2_b32 v34, v44, v45 offset0:140 offset1:206
	ds_write2_b32 v35, v46, v47 offset0:16 offset1:82
	ds_write2_b32 v35, v48, v49 offset0:148 offset1:214
	ds_write2_b32 v36, v50, v51 offset0:24 offset1:90
	ds_write2_b32 v36, v52, v53 offset0:156 offset1:222
	ds_write2_b32 v37, v54, v55 offset0:32 offset1:98
	ds_write2_b32 v37, v56, v57 offset0:164 offset1:230
	ds_write2_b32 v38, v58, v59 offset0:40 offset1:106
	ds_write2_b32 v38, v60, v61 offset0:172 offset1:238
	ds_write2_b32 v39, v62, v63 offset0:48 offset1:114
	ds_write2_b32 v39, v64, v65 offset0:180 offset1:246
	ds_write2_b32 v40, v66, v67 offset0:56 offset1:122
	ds_write2_b32 v40, v68, v69 offset0:188 offset1:254
	s_waitcnt lgkmcnt(0)
	ds_read2_b32 v[48:49], v31 offset1:16
	ds_read2_b32 v[50:51], v31 offset0:33 offset1:49
	ds_read2_b32 v[52:53], v31 offset0:66 offset1:82
	ds_read2_b32 v[54:55], v31 offset0:99 offset1:115
	ds_read2_b32 v[56:57], v31 offset0:132 offset1:148
	ds_read2_b32 v[58:59], v31 offset0:165 offset1:181
	ds_read2_b32 v[60:61], v31 offset0:198 offset1:214
	ds_read2_b32 v[62:63], v31 offset0:231 offset1:247
	ds_read2_b32 v[64:65], v41 offset0:8 offset1:24
	ds_read2_b32 v[66:67], v41 offset0:41 offset1:57
	ds_read2_b32 v[68:69], v41 offset0:74 offset1:90
	ds_read2_b32 v[70:71], v41 offset0:107 offset1:123
	ds_read2_b32 v[72:73], v41 offset0:140 offset1:156
	ds_read2_b32 v[74:75], v41 offset0:173 offset1:189
	ds_read2_b32 v[76:77], v41 offset0:206 offset1:222
	ds_read2_b32 v[78:79], v41 offset0:239 offset1:255
	s_addc_u32 s5, s8, s62
	v_mov_b32_e32 v42, 0
	v_mov_b32_e32 v43, 0
	v_mov_b32_e32 v44, 0
	v_mov_b32_e32 v45, 0
	v_lshl_add_u64 v[46:47], s[4:5], 0, v[2:3]
	s_waitcnt lgkmcnt(14)
	v_cvt_scalef32_pk_fp8_f32 v42, v48, v50, s49
	s_waitcnt lgkmcnt(10)
	v_cvt_scalef32_pk_fp8_f32 v43, v56, v58, s49
	s_waitcnt lgkmcnt(6)
	v_cvt_scalef32_pk_fp8_f32 v44, v64, v66, s49
	s_waitcnt lgkmcnt(2)
	v_cvt_scalef32_pk_fp8_f32 v45, v72, v74, s49
	v_cvt_scalef32_pk_fp8_f32 v42, v52, v54, s49 op_sel:[0,0,0,1]
	v_cvt_scalef32_pk_fp8_f32 v43, v60, v62, s49 op_sel:[0,0,0,1]
	v_cvt_scalef32_pk_fp8_f32 v44, v68, v70, s49 op_sel:[0,0,0,1]
	s_waitcnt lgkmcnt(0)
	v_cvt_scalef32_pk_fp8_f32 v45, v76, v78, s49 op_sel:[0,0,0,1]
	v_lshl_add_u64 v[80:81], v[46:47], 0, v[4:5]
	global_store_dwordx4 v[80:81], v[42:45], off
	v_lshl_add_u64 v[46:47], v[46:47], 0, v[6:7]
	s_nop 0
	v_mov_b32_e32 v42, 0
	v_mov_b32_e32 v43, 0
	v_mov_b32_e32 v44, 0
	v_mov_b32_e32 v45, 0
	v_cvt_scalef32_pk_fp8_f32 v42, v49, v51, s49
	v_cvt_scalef32_pk_fp8_f32 v43, v57, v59, s49
	v_cvt_scalef32_pk_fp8_f32 v44, v65, v67, s49
	v_cvt_scalef32_pk_fp8_f32 v45, v73, v75, s49
	v_cvt_scalef32_pk_fp8_f32 v42, v53, v55, s49 op_sel:[0,0,0,1]
	v_cvt_scalef32_pk_fp8_f32 v43, v61, v63, s49 op_sel:[0,0,0,1]
	v_cvt_scalef32_pk_fp8_f32 v44, v69, v71, s49 op_sel:[0,0,0,1]
	v_cvt_scalef32_pk_fp8_f32 v45, v77, v79, s49 op_sel:[0,0,0,1]
	global_store_dwordx4 v[46:47], v[42:45], off
	s_waitcnt lgkmcnt(0)
	s_branch .LBB0_26
